# static priority raise for waves 4-7 also during the m2 gmlp / ssd_s1 item loop
# baseline (speedup 1.0000x reference)
.LBB0_612:
	v_readlane_b32 s4, v243, 9
	v_readlane_b32 s5, v243, 10
	v_mov_b32_e32 v63, v1
	s_mov_b64 s[90:91], s[0:1]
	s_mov_b64 s[6:7], -1
	s_and_b64 vcc, exec, s[4:5]
	s_cbranch_vccz .LBB0_663
	v_readlane_b32 s4, v243, 11
	v_readlane_b32 s5, v243, 12
	s_andn2_b64 vcc, exec, s[4:5]
	s_cbranch_vccnz .LBB0_655
	v_and_b32_e32 v3, 63, v63
	v_ashrrev_i32_e32 v60, 6, v63
	v_lshlrev_b32_e32 v2, 4, v3
	v_lshl_or_b32 v2, v60, 10, v2
	v_readlane_b32 s4, v242, 2
	v_readlane_b32 s2, v242, 3
	v_ashrrev_i32_e32 v70, 5, v63
	v_add_u32_e32 v65, s4, v2
	v_add_u32_e32 v67, s2, v2
	v_and_b32_e32 v2, 31, v63
	s_movk_i32 s2, 0x100
	v_cmp_gt_u32_e64 s[22:23], 16, v2
	v_lshlrev_b32_e32 v69, 3, v2
	v_lshlrev_b32_e32 v4, 7, v63
	v_cmp_gt_i32_e64 s[24:25], s2, v70
	v_lshlrev_b32_e32 v7, 4, v2
	v_bfe_u32 v9, v63, 4, 2
	v_and_b32_e32 v13, 15, v63
	v_and_b32_e32 v2, 3, v60
	s_movk_i32 s2, 0x1020
	v_and_b32_e32 v5, 0x400, v4
	v_lshlrev_b32_e32 v4, 6, v2
	v_mad_u32_u24 v8, v9, s2, 0
	v_lshlrev_b32_e32 v15, 1, v13
	v_add3_u32 v147, v8, v4, v15
	v_lshlrev_b32_e32 v4, 9, v9
	v_lshlrev_b32_e32 v2, 5, v2
	v_lshlrev_b32_e32 v17, 4, v60
	v_or3_b32 v2, v2, v13, v4
	v_or_b32_e32 v74, v17, v13
	v_or_b32_e32 v13, 15, v17
	v_ashrrev_i32_e32 v17, 31, v63
	s_movk_i32 s2, 0x80
	v_lshrrev_b32_e32 v17, 27, v17
	v_cmp_gt_i32_e64 s[26:27], s2, v60
	v_add_u32_e32 v17, v13, v17
	v_cmp_lt_i32_e64 s[28:29], s65, v13
	v_lshlrev_b32_e32 v13, 2, v70
	s_movk_i32 s2, 0x204
	v_lshlrev_b32_e32 v62, 2, v3
	v_cmp_eq_u32_e64 s[8:9], 0, v3
	v_cmp_gt_u32_e64 s[10:11], 2, v3
	v_cmp_gt_u32_e64 s[12:13], 4, v3
	v_cmp_gt_u32_e64 s[14:15], 8, v3
	v_cmp_gt_u32_e64 s[16:17], 16, v3
	v_cmp_gt_u32_e64 s[18:19], 32, v3
	v_cmp_eq_u32_e64 s[20:21], 63, v3
	v_add_u32_e32 v145, s4, v5
	v_add3_u32 v157, v5, v13, s4
	v_mul_lo_u32 v5, v70, s2
	v_lshlrev_b32_e32 v78, 3, v3
	v_mul_u32_u24_e32 v3, 0x1020, v9
	v_ashrrev_i32_e32 v72, 8, v63
	v_add3_u32 v158, v5, v7, 0
	v_mul_lo_u32 v5, v60, s2
	v_or_b32_e32 v3, v3, v15
	s_add_i32 s2, 0, 0x80
	v_lshlrev_b32_e32 v6, 7, v72
	v_lshlrev_b32_e32 v30, 2, v9
	v_add_u32_e32 v163, s2, v3
	s_add_i32 s2, 0, 0x100
	v_add3_u32 v148, v8, v6, v15
	v_or_b32_e32 v4, 0x800, v2
	v_or_b32_e32 v6, 0x880, v2
	v_or_b32_e32 v8, 0x900, v2
	v_or_b32_e32 v10, 0x980, v2
	v_or_b32_e32 v12, 0x1000, v2
	v_or_b32_e32 v14, 0x1080, v2
	v_or_b32_e32 v16, 0x1100, v2
	v_or_b32_e32 v18, 0x1180, v2
	v_or_b32_e32 v20, 0x1800, v2
	v_or_b32_e32 v22, 0x1880, v2
	v_or_b32_e32 v24, 0x1900, v2
	v_or_b32_e32 v26, 0x1980, v2
	v_ashrrev_i32_e32 v17, 5, v17
	v_ashrrev_i32_e32 v75, 31, v74
	v_lshlrev_b32_e32 v28, 3, v9
	v_or_b32_e32 v32, 16, v30
	v_or_b32_e32 v34, 32, v30
	v_or_b32_e32 v36, 48, v30
	v_or_b32_e32 v38, 64, v30
	v_or_b32_e32 v40, 0x50, v30
	v_or_b32_e32 v42, 0x60, v30
	v_or_b32_e32 v44, 0x70, v30
	v_or_b32_e32 v46, 0x80, v30
	v_or_b32_e32 v48, 0x90, v30
	v_or_b32_e32 v50, 0xa0, v30
	v_or_b32_e32 v52, 0xb0, v30
	v_or_b32_e32 v54, 0xc0, v30
	v_or_b32_e32 v56, 0xd0, v30
	v_or_b32_e32 v58, 0xe0, v30
	v_or_b32_e32 v142, 0xf0, v30
	v_or_b32_e32 v82, 0x80, v2
	v_or_b32_e32 v84, 0x100, v2
	v_or_b32_e32 v86, 0x180, v2
	v_add_u32_e32 v164, s2, v3
	s_add_i32 s2, 0, 0x180
	v_cmp_gt_i32_e64 s[6:7], 2, v60
	v_or_b32_e32 v64, 1, v62
	v_or_b32_e32 v66, 2, v62
	v_or_b32_e32 v68, 3, v62
	v_add_u32_e32 v144, 0x80, v69
	v_add_u32_e32 v146, 0x880, v69
	v_add_u32_e32 v149, 0x10300, v147
	v_add_u32_e32 v150, 0x10200, v148
	v_add_u32_e32 v151, 0x14380, v147
	v_add_u32_e32 v152, 0x14280, v148
	v_add_u32_e32 v153, 0x18400, v147
	v_add_u32_e32 v154, 0x18300, v148
	v_add_u32_e32 v155, 0x1c480, v147
	v_add_u32_e32 v156, 0x1c380, v148
	v_ashrrev_i32_e32 v73, 31, v72
	v_lshlrev_b64 v[76:77], 8, v[74:75]
	v_ashrrev_i32_e32 v71, 31, v70
	v_add_u32_e32 v159, -16, v60
	v_add3_u32 v160, v5, v78, 0
	v_mov_b32_e32 v79, v11
	v_ashrrev_i32_e32 v61, 31, v60
	v_add_u32_e32 v161, 1, v17
	v_add_u32_e32 v162, 0, v3
	v_add_u32_e32 v165, s2, v3
	v_lshlrev_b32_e32 v80, 2, v2
	v_lshlrev_b32_e32 v82, 2, v82
	v_lshlrev_b32_e32 v84, 2, v84
	v_lshlrev_b32_e32 v86, 2, v86
	v_lshlrev_b32_e32 v88, 2, v4
	v_lshlrev_b32_e32 v90, 2, v6
	v_lshlrev_b32_e32 v92, 2, v8
	v_lshlrev_b32_e32 v94, 2, v10
	v_lshlrev_b32_e32 v96, 2, v12
	v_lshlrev_b32_e32 v98, 2, v14
	v_lshlrev_b32_e32 v100, 2, v16
	v_lshlrev_b32_e32 v102, 2, v18
	v_lshlrev_b32_e32 v104, 2, v20
	v_lshlrev_b32_e32 v106, 2, v22
	v_lshlrev_b32_e32 v108, 2, v24
	v_lshlrev_b32_e32 v110, 2, v26
	v_lshlrev_b32_e32 v10, 1, v28
	v_lshlrev_b32_e32 v112, 1, v30
	v_lshlrev_b32_e32 v114, 1, v32
	v_lshlrev_b32_e32 v116, 1, v34
	v_lshlrev_b32_e32 v118, 1, v36
	v_lshlrev_b32_e32 v120, 1, v38
	v_lshlrev_b32_e32 v122, 1, v40
	v_lshlrev_b32_e32 v124, 1, v42
	v_lshlrev_b32_e32 v126, 1, v44
	v_lshlrev_b32_e32 v128, 1, v46
	v_lshlrev_b32_e32 v130, 1, v48
	v_lshlrev_b32_e32 v132, 1, v50
	v_lshlrev_b32_e32 v134, 1, v52
	v_lshlrev_b32_e32 v136, 1, v54
	v_lshlrev_b32_e32 v138, 1, v56
	v_lshlrev_b32_e32 v140, 1, v58
	v_lshlrev_b32_e32 v142, 1, v142
	v_readlane_b32 s46, v243, 52
	v_readlane_b32 s47, v243, 50
	v_readlane_b32 s96, v243, 14
	v_readfirstlane_b32 s2, v1
	s_bitcmp1_b32 s2, 8
	s_cbranch_scc0 .Lm2_prio_skip
	s_setprio 2
.Lm2_prio_skip:
	s_branch .LBB0_617
.LBB0_615:
	s_or_b64 exec, exec, s[30:31]
	global_load_dword v22, v[30:31], off offset:1536
	global_load_dwordx2 v[20:21], v[26:27], off offset:2944
	global_load_dwordx2 v[244:245], v[26:27], off offset:2976
	global_load_dwordx2 v[246:247], v[26:27], off offset:3008
	global_load_dwordx2 v[248:249], v[26:27], off offset:3040
	v_mov_b32_e32 v137, v11
	v_mov_b32_e32 v139, v11
	v_mov_b32_e32 v141, v11
	v_mov_b32_e32 v143, v11
	s_waitcnt vmcnt(4)
	v_add_f32_e32 v17, v22, v17
	s_waitcnt vmcnt(3)
	v_lshlrev_b32_e32 v23, 16, v20
	v_and_b32_e32 v20, 0xffff0000, v20
	v_mul_f32_e32 v17, v17, v20
	v_lshlrev_b32_e32 v20, 16, v21
	v_add_f32_e32 v18, v22, v18
	v_add_f32_e32 v16, v22, v16
	v_mul_f32_e32 v18, v18, v20
	v_and_b32_e32 v20, 0xffff0000, v21
	v_add_f32_e32 v19, v22, v19
	v_mul_f32_e32 v16, v16, v23
	v_mul_f32_e32 v19, v19, v20
	v_cvt_pk_bf16_f32 v16, v16, v17
	v_cvt_pk_bf16_f32 v17, v18, v19
	v_lshl_add_u64 v[18:19], v[24:25], 0, v[136:137]
	global_store_dwordx2 v[18:19], v[16:17], off
	s_nop 0
	v_add_f32_e32 v13, v22, v13
	v_add_f32_e32 v14, v22, v14
	v_add_f32_e32 v12, v22, v12
	v_add_f32_e32 v15, v22, v15
	v_add_f32_e32 v7, v22, v7
	v_add_f32_e32 v8, v22, v8
	v_add_f32_e32 v6, v22, v6
	v_add_f32_e32 v9, v22, v9
	v_add_f32_e32 v3, v22, v3
	v_add_f32_e32 v4, v22, v4
	v_add_f32_e32 v2, v22, v2
	v_add_f32_e32 v5, v22, v5
	s_waitcnt vmcnt(2)
	v_lshlrev_b32_e32 v18, 16, v244
	v_and_b32_e32 v16, 0xffff0000, v244
	v_mul_f32_e32 v13, v13, v16
	v_lshlrev_b32_e32 v16, 16, v245
	v_mul_f32_e32 v14, v14, v16
	v_and_b32_e32 v16, 0xffff0000, v245
	v_mul_f32_e32 v12, v12, v18
	v_mul_f32_e32 v15, v15, v16
	v_cvt_pk_bf16_f32 v12, v12, v13
	v_cvt_pk_bf16_f32 v13, v14, v15
	v_lshl_add_u64 v[14:15], v[24:25], 0, v[138:139]
	global_store_dwordx2 v[14:15], v[12:13], off
	s_nop 0
	s_waitcnt vmcnt(1)
	v_lshlrev_b32_e32 v14, 16, v246
	v_and_b32_e32 v12, 0xffff0000, v246
	v_mul_f32_e32 v7, v7, v12
	v_lshlrev_b32_e32 v12, 16, v247
	v_mul_f32_e32 v8, v8, v12
	v_and_b32_e32 v12, 0xffff0000, v247
	v_mul_f32_e32 v6, v6, v14
	v_mul_f32_e32 v9, v9, v12
	v_cvt_pk_bf16_f32 v6, v6, v7
	v_cvt_pk_bf16_f32 v7, v8, v9
	v_lshl_add_u64 v[8:9], v[24:25], 0, v[140:141]
	global_store_dwordx2 v[8:9], v[6:7], off
	s_nop 0
	s_waitcnt vmcnt(0)
	v_lshlrev_b32_e32 v8, 16, v248
	v_and_b32_e32 v6, 0xffff0000, v248
	v_mul_f32_e32 v3, v3, v6
	v_lshlrev_b32_e32 v6, 16, v249
	v_mul_f32_e32 v4, v4, v6
	v_and_b32_e32 v6, 0xffff0000, v249
	v_mul_f32_e32 v2, v2, v8
	v_mul_f32_e32 v5, v5, v6
	v_cvt_pk_bf16_f32 v2, v2, v3
	v_cvt_pk_bf16_f32 v3, v4, v5
	v_lshl_add_u64 v[4:5], v[24:25], 0, v[142:143]
	global_store_dwordx2 v[4:5], v[2:3], off
	s_barrier

.LBB0_655:
	s_setprio 0
	v_readfirstlane_b32 s2, v63
	s_ashr_i32 s4, s2, 6
	v_readlane_b32 s2, v243, 15
	s_add_i32 s2, s4, s2
	s_cmpk_gt_i32 s2, 0x7ff
	v_readlane_b32 s76, v242, 15
	s_barrier
	v_readlane_b32 s77, v242, 16
	s_cbranch_scc1 .LBB0_662
	v_and_b32_e32 v3, 63, v63
	s_mulk_i32 s4, 0x2200
	v_bfe_u32 v6, v63, 3, 3
	v_lshlrev_b32_e32 v2, 3, v3
	s_add_i32 s4, s4, 0
	v_and_b32_e32 v5, 15, v63
	v_and_b32_e32 v4, 56, v2
	v_mul_u32_u24_e32 v12, 0xc00, v6
	s_movk_i32 s5, 0xc00
	v_bfe_u32 v7, v63, 4, 2
	v_lshl_add_u32 v13, v4, 1, s4
	v_mul_u32_u24_e32 v15, 0x84, v6
	v_or_b32_e32 v14, 0x18000, v12
	v_mad_u32_u24 v16, v6, s5, v209
	v_mad_u32_u24 v18, v6, s5, v210
	v_mad_u32_u24 v20, v6, s5, v211
	v_lshlrev_b32_e32 v22, 3, v7
	v_mul_u32_u24_e32 v24, 0xc00, v5
	v_or_b32_e32 v28, 0x800, v2
	v_or_b32_e32 v30, 0xa00, v2
	v_or_b32_e32 v6, 48, v3
	v_lshlrev_b32_e32 v5, 1, v5
	v_mul_u32_u24_e32 v10, 0x210, v7
	v_mul_u32_u24_e32 v6, 0xc00, v6
	v_add3_u32 v7, s4, v5, v10
	v_lshlrev_b32_e32 v8, 4, v3
	v_mov_b32_e32 v9, v11
	v_add3_u32 v34, s4, v10, v5
	v_lshlrev_b32_e32 v10, 1, v4
	v_lshlrev_b32_e32 v12, 1, v12
	v_add_u32_e32 v35, v13, v15
	v_lshlrev_b32_e32 v14, 1, v14
	v_lshlrev_b32_e32 v16, 1, v16
	v_lshlrev_b32_e32 v18, 1, v18
	v_lshlrev_b32_e32 v20, 1, v20
	v_lshlrev_b32_e32 v22, 1, v22
	v_lshlrev_b32_e32 v24, 1, v24
	v_lshlrev_b32_e32 v26, 1, v2
	v_lshlrev_b32_e32 v36, 1, v28
	v_lshlrev_b32_e32 v37, 1, v30
	s_branch .LBB0_658
